# spatial gating epilogue de-serialised: 8 bias + 16 u loads of a unit requested together after the last MFMA, counted waits, stores not waited on
# speedup vs baseline: 1.0009x; 1.0009x over previous
.LBB11_1433:
	s_waitcnt lgkmcnt(0)
	s_waitcnt lgkmcnt(0)
	s_barrier
	ds_read_u16 v70, v175 offset:520
	ds_read_u16 v71, v175 offset:1040
	ds_read_u16 v74, v175 offset:1560
	ds_read_u16 v72, v175 offset:2080
	ds_read_u16 v75, v175 offset:2600
	ds_read_u16 v73, v175 offset:3120
	ds_read_u16 v76, v175 offset:3640
	ds_read_u16 v77, v175
	ds_read_u16 v78, v175 offset:32
	ds_read_u16 v79, v175 offset:552
	ds_read_u16 v80, v175 offset:1072
	ds_read_u16 v81, v175 offset:1592
	ds_read_u16 v82, v175 offset:2112
	ds_read_u16 v83, v175 offset:2632
	ds_read_u16 v84, v175 offset:3152
	ds_read_u16 v85, v175 offset:3672
	ds_read_b128 v[66:69], v193
	s_waitcnt lgkmcnt(10)
	v_perm_b32 v73, v76, v73, s85
	v_perm_b32 v72, v75, v72, s85
	v_perm_b32 v71, v74, v71, s85
	s_waitcnt lgkmcnt(9)
	v_perm_b32 v70, v70, v77, s85
	s_waitcnt lgkmcnt(1)
	v_perm_b32 v77, v85, v84, s85
	v_perm_b32 v76, v83, v82, s85
	v_perm_b32 v75, v81, v80, s85
	v_perm_b32 v74, v79, v78, s85
	ds_read_b128 v[98:101], v193 offset:21760
	s_waitcnt lgkmcnt(1)
	v_mfma_f32_16x16x32_bf16 v[126:129], v[70:73], v[66:69], 0
	ds_read_b128 v[82:85], v193 offset:13056
	ds_read_b128 v[90:93], v193 offset:17408
	s_and_b32 s16, s6, 0xffffff80
	v_mfma_f32_16x16x32_bf16 v[122:125], v[74:77], v[66:69], 0
	ds_read_b128 v[66:69], v193 offset:4352
	s_add_i32 s16, s16, s8
	s_add_i32 s18, s18, 16
	s_waitcnt lgkmcnt(3)
	v_mfma_f32_16x16x32_bf16 v[166:169], v[70:73], v[98:101], 0
	s_andn2_b64 vcc, exec, s[14:15]
	s_mov_b32 s6, s19
	v_mfma_f32_16x16x32_bf16 v[194:197], v[74:77], v[98:101], 0
	ds_read_b128 v[98:101], v193 offset:26112
	s_waitcnt lgkmcnt(1)
	v_mfma_f32_16x16x32_bf16 v[118:121], v[70:73], v[66:69], 0
	v_mfma_f32_16x16x32_bf16 v[114:117], v[74:77], v[66:69], 0
	ds_read_b128 v[66:69], v193 offset:8704
	s_waitcnt lgkmcnt(1)
	v_mfma_f32_16x16x32_bf16 v[214:217], v[70:73], v[98:101], 0
	v_mfma_f32_16x16x32_bf16 v[218:221], v[74:77], v[98:101], 0
	ds_read_b128 v[98:101], v193 offset:30464
	s_waitcnt lgkmcnt(1)
	v_mfma_f32_16x16x32_bf16 v[78:81], v[70:73], v[66:69], 0
	v_mfma_f32_16x16x32_bf16 v[66:69], v[74:77], v[66:69], 0
	v_mfma_f32_16x16x32_bf16 v[86:89], v[70:73], v[82:85], 0
	v_mfma_f32_16x16x32_bf16 v[82:85], v[74:77], v[82:85], 0
	v_mfma_f32_16x16x32_bf16 v[94:97], v[70:73], v[90:93], 0
	v_mfma_f32_16x16x32_bf16 v[90:93], v[74:77], v[90:93], 0
	s_waitcnt lgkmcnt(0)
	v_mfma_f32_16x16x32_bf16 v[70:73], v[70:73], v[98:101], 0
	v_mfma_f32_16x16x32_bf16 v[74:77], v[74:77], v[98:101], 0
	ds_read_u16 v102, v175 offset:16640
	ds_read_u16 v103, v175 offset:17160
	ds_read_u16 v104, v175 offset:17680
	ds_read_u16 v105, v175 offset:18200
	ds_read_u16 v106, v175 offset:18720
	ds_read_u16 v107, v175 offset:19240
	ds_read_u16 v108, v175 offset:19760
	ds_read_u16 v109, v175 offset:20280
	ds_read_u16 v170, v175 offset:16672
	ds_read_u16 v171, v175 offset:17192
	ds_read_u16 v213, v175 offset:17712
	ds_read_u16 v226, v175 offset:18232
	ds_read_u16 v227, v175 offset:18752
	ds_read_u16 v228, v175 offset:19272
	ds_read_u16 v229, v175 offset:19792
	ds_read_u16 v230, v175 offset:20312
	ds_read_b128 v[98:101], v193 offset:8768
	s_waitcnt lgkmcnt(9)
	v_perm_b32 v225, v109, v108, s85
	v_perm_b32 v224, v107, v106, s85
	v_perm_b32 v223, v105, v104, s85
	v_perm_b32 v222, v103, v102, s85
	s_waitcnt lgkmcnt(0)
	s_nop 0
	v_mfma_f32_16x16x32_bf16 v[110:113], v[222:225], v[98:101], v[78:81]
	s_nop 2
	v_perm_b32 v81, v230, v229, s85
	v_perm_b32 v80, v228, v227, s85
	v_perm_b32 v79, v226, v213, s85
	v_perm_b32 v78, v171, v170, s85
	s_nop 1
	v_mfma_f32_16x16x32_bf16 v[106:109], v[78:81], v[98:101], v[66:69]
	s_nop 2
	ds_read_b128 v[66:69], v193 offset:13120
	s_waitcnt lgkmcnt(0)
	v_mfma_f32_16x16x32_bf16 v[102:105], v[222:225], v[66:69], v[86:89]
	s_nop 2
	ds_read_b128 v[86:89], v193 offset:21824
	v_mfma_f32_16x16x32_bf16 v[98:101], v[78:81], v[66:69], v[82:85]
	ds_read_b128 v[66:69], v193 offset:17472
	s_waitcnt lgkmcnt(1)
	v_mfma_f32_16x16x32_bf16 v[166:169], v[222:225], v[86:89], v[166:169]
	v_mfma_f32_16x16x32_bf16 v[194:197], v[78:81], v[86:89], v[194:197]
	ds_read_b128 v[86:89], v193 offset:26176
	s_waitcnt lgkmcnt(0)
	v_mfma_f32_16x16x32_bf16 v[214:217], v[222:225], v[86:89], v[214:217]
	v_mfma_f32_16x16x32_bf16 v[218:221], v[78:81], v[86:89], v[218:221]
	ds_read_b128 v[86:89], v193 offset:30528
	v_mfma_f32_16x16x32_bf16 v[82:85], v[222:225], v[66:69], v[94:97]
	v_mfma_f32_16x16x32_bf16 v[66:69], v[78:81], v[66:69], v[90:93]
	s_waitcnt lgkmcnt(0)
	v_mfma_f32_16x16x32_bf16 v[70:73], v[222:225], v[86:89], v[70:73]
	v_mfma_f32_16x16x32_bf16 v[74:77], v[78:81], v[86:89], v[74:77]
	ds_read_u16 v86, v175 offset:33280
	ds_read_u16 v87, v175 offset:33800
	ds_read_u16 v88, v175 offset:34320
	ds_read_u16 v89, v175 offset:34840
	ds_read_u16 v90, v175 offset:35360
	ds_read_u16 v91, v175 offset:35880
	ds_read_u16 v92, v175 offset:36400
	ds_read_u16 v93, v175 offset:36920
	ds_read_u16 v170, v175 offset:33312
	ds_read_u16 v171, v175 offset:33832
	ds_read_u16 v213, v175 offset:34352
	ds_read_u16 v226, v175 offset:34872
	ds_read_u16 v227, v175 offset:35392
	ds_read_u16 v228, v175 offset:35912
	ds_read_u16 v229, v175 offset:36432
	ds_read_u16 v230, v175 offset:36952
	ds_read_b128 v[78:81], v193 offset:17536
	s_waitcnt lgkmcnt(9)
	v_perm_b32 v225, v93, v92, s85
	s_waitcnt lgkmcnt(3)
	v_perm_b32 v228, v228, v227, s85
	v_perm_b32 v227, v226, v213, s85
	s_waitcnt lgkmcnt(1)
	v_perm_b32 v229, v230, v229, s85
	v_perm_b32 v226, v171, v170, s85
	v_perm_b32 v224, v91, v90, s85
	v_perm_b32 v223, v89, v88, s85
	v_perm_b32 v222, v87, v86, s85
	s_waitcnt lgkmcnt(0)
	v_mfma_f32_16x16x32_bf16 v[90:93], v[226:229], v[78:81], v[66:69]
	s_nop 2
	ds_read_b128 v[66:69], v193 offset:21888
	v_mfma_f32_16x16x32_bf16 v[94:97], v[222:225], v[78:81], v[82:85]
	s_waitcnt lgkmcnt(0)
	v_mfma_f32_16x16x32_bf16 v[86:89], v[222:225], v[66:69], v[166:169]
	v_mfma_f32_16x16x32_bf16 v[82:85], v[226:229], v[66:69], v[194:197]
	ds_read_b128 v[66:69], v193 offset:26240
	s_nop 0
	ds_read_b128 v[166:169], v193 offset:30592
	s_waitcnt lgkmcnt(1)
	v_mfma_f32_16x16x32_bf16 v[78:81], v[222:225], v[66:69], v[214:217]
	v_mfma_f32_16x16x32_bf16 v[66:69], v[226:229], v[66:69], v[218:221]
	s_waitcnt lgkmcnt(0)
	v_mfma_f32_16x16x32_bf16 v[70:73], v[222:225], v[166:169], v[70:73]
	v_mfma_f32_16x16x32_bf16 v[166:169], v[226:229], v[166:169], v[74:77]
	ds_read_u16 v170, v175 offset:49920
	ds_read_u16 v171, v175 offset:50440
	ds_read_u16 v194, v175 offset:50960
	ds_read_u16 v195, v175 offset:51480
	ds_read_u16 v196, v175 offset:52000
	ds_read_u16 v213, v175 offset:52520
	ds_read_u16 v197, v175 offset:53040
	ds_read_u16 v214, v175 offset:53560
	ds_read_u16 v218, v175 offset:49952
	ds_read_u16 v219, v175 offset:50472
	ds_read_u16 v215, v175 offset:50992
	ds_read_u16 v220, v175 offset:51512
	ds_read_u16 v216, v175 offset:52032
	ds_read_u16 v221, v175 offset:52552
	ds_read_u16 v217, v175 offset:53072
	ds_read_u16 v222, v175 offset:53592
	ds_read_b128 v[74:77], v193 offset:26304
	s_waitcnt lgkmcnt(9)
	v_perm_b32 v197, v214, v197, s85
	v_perm_b32 v196, v213, v196, s85
	v_perm_b32 v195, v195, v194, s85
	v_perm_b32 v194, v171, v170, s85
	s_waitcnt lgkmcnt(1)
	v_perm_b32 v217, v222, v217, s85
	v_perm_b32 v216, v221, v216, s85
	v_perm_b32 v215, v220, v215, s85
	v_perm_b32 v214, v219, v218, s85
	s_waitcnt lgkmcnt(0)
	v_mfma_f32_16x16x32_bf16 v[78:81], v[194:197], v[74:77], v[78:81]
	v_mfma_f32_16x16x32_bf16 v[74:77], v[214:217], v[74:77], v[66:69]
	s_nop 2
	ds_read_b128 v[66:69], v193 offset:30656
	s_waitcnt lgkmcnt(0)
	v_mfma_f32_16x16x32_bf16 v[70:73], v[194:197], v[66:69], v[70:73]
	v_mfma_f32_16x16x32_bf16 v[66:69], v[214:217], v[66:69], v[166:169]
	global_load_dword v196, v[154:155], off
	v_or_b32_e32 v218, s16, v172
	v_ashrrev_i32_e32 v219, 31, v218
	v_lshlrev_b64 v[218:219], 13, v[218:219]
	v_lshl_add_u64 v[218:219], v[160:161], 0, v[218:219]
	global_load_dwordx2 v[220:221], v[218:219], off offset:32
	global_load_dwordx2 v[218:219], v[218:219], off
	global_load_dword v197, v[156:157], off offset:64
	v_or_b32_e32 v222, s16, v176
	v_ashrrev_i32_e32 v223, 31, v222
	v_lshlrev_b64 v[222:223], 13, v[222:223]
	v_lshl_add_u64 v[222:223], v[160:161], 0, v[222:223]
	global_load_dwordx2 v[224:225], v[222:223], off offset:32
	global_load_dwordx2 v[222:223], v[222:223], off
	global_load_dword v213, v[156:157], off offset:128
	v_or_b32_e32 v226, s16, v177
	v_ashrrev_i32_e32 v227, 31, v226
	v_lshlrev_b64 v[226:227], 13, v[226:227]
	v_lshl_add_u64 v[226:227], v[160:161], 0, v[226:227]
	global_load_dwordx2 v[228:229], v[226:227], off offset:32
	global_load_dwordx2 v[226:227], v[226:227], off
	global_load_dword v249, v[156:157], off offset:192
	v_or_b32_e32 v230, s16, v178
	v_ashrrev_i32_e32 v231, 31, v230
	v_lshlrev_b64 v[230:231], 13, v[230:231]
	v_lshl_add_u64 v[230:231], v[160:161], 0, v[230:231]
	global_load_dwordx2 v[232:233], v[230:231], off offset:32
	global_load_dwordx2 v[230:231], v[230:231], off
	global_load_dword v214, v[156:157], off offset:256
	v_or_b32_e32 v234, s16, v179
	v_ashrrev_i32_e32 v235, 31, v234
	v_lshlrev_b64 v[234:235], 13, v[234:235]
	v_lshl_add_u64 v[234:235], v[160:161], 0, v[234:235]
	global_load_dwordx2 v[236:237], v[234:235], off offset:32
	global_load_dwordx2 v[234:235], v[234:235], off
	global_load_dword v215, v[156:157], off offset:320
	v_or_b32_e32 v238, s16, v180
	v_ashrrev_i32_e32 v239, 31, v238
	v_lshlrev_b64 v[238:239], 13, v[238:239]
	v_lshl_add_u64 v[238:239], v[160:161], 0, v[238:239]
	global_load_dwordx2 v[240:241], v[238:239], off offset:32
	global_load_dwordx2 v[238:239], v[238:239], off
	global_load_dword v216, v[156:157], off offset:384
	v_or_b32_e32 v250, s16, v181
	v_ashrrev_i32_e32 v251, 31, v250
	v_lshlrev_b64 v[250:251], 13, v[250:251]
	v_lshl_add_u64 v[250:251], v[160:161], 0, v[250:251]
	global_load_dwordx2 v[252:253], v[250:251], off offset:32
	global_load_dwordx2 v[250:251], v[250:251], off
	global_load_dword v217, v[156:157], off offset:448
	v_or_b32_e32 v254, s16, v174
	v_ashrrev_i32_e32 v255, 31, v254
	v_lshlrev_b64 v[254:255], 13, v[254:255]
	v_lshl_add_u64 v[254:255], v[160:161], 0, v[254:255]
	global_load_dwordx2 v[194:195], v[254:255], off offset:32
	global_load_dwordx2 v[254:255], v[254:255], off
	s_waitcnt vmcnt(21)
	v_add_f32_e32 v126, v126, v196
	v_add_f32_e32 v127, v127, v196
	v_add_f32_e32 v128, v128, v196
	v_add_f32_e32 v129, v129, v196
	v_lshlrev_b32_e32 v168, 16, v218
	v_and_b32_e32 v169, 0xffff0000, v218
	v_mul_f32_e32 v126, v126, v168
	v_mul_f32_e32 v127, v127, v169
	v_lshlrev_b32_e32 v168, 16, v219
	v_and_b32_e32 v169, 0xffff0000, v219
	v_mul_f32_e32 v128, v128, v168
	v_mul_f32_e32 v129, v129, v169
	v_cvt_pk_bf16_f32 v126, v126, v127
	v_cvt_pk_bf16_f32 v127, v128, v129
	v_or_b32_e32 v128, s16, v172
	v_ashrrev_i32_e32 v129, 31, v128
	v_lshlrev_b64 v[128:129], 12, v[128:129]
	v_lshl_add_u64 v[128:129], v[162:163], 0, v[128:129]
	global_store_dwordx2 v[128:129], v[126:127], off
	v_add_f32_e32 v122, v122, v196
	v_add_f32_e32 v123, v123, v196
	v_add_f32_e32 v124, v124, v196
	v_add_f32_e32 v125, v125, v196
	v_lshlrev_b32_e32 v168, 16, v220
	v_and_b32_e32 v169, 0xffff0000, v220
	v_mul_f32_e32 v122, v122, v168
	v_mul_f32_e32 v123, v123, v169
	v_lshlrev_b32_e32 v168, 16, v221
	v_and_b32_e32 v169, 0xffff0000, v221
	v_mul_f32_e32 v124, v124, v168
	v_mul_f32_e32 v125, v125, v169
	v_cvt_pk_bf16_f32 v122, v122, v123
	v_cvt_pk_bf16_f32 v123, v124, v125
	global_store_dwordx2 v[128:129], v[122:123], off offset:32
	s_waitcnt vmcnt(20)
	v_add_f32_e32 v118, v118, v197
	v_add_f32_e32 v119, v119, v197
	v_add_f32_e32 v120, v120, v197
	v_add_f32_e32 v121, v121, v197
	v_lshlrev_b32_e32 v168, 16, v222
	v_and_b32_e32 v169, 0xffff0000, v222
	v_mul_f32_e32 v118, v118, v168
	v_mul_f32_e32 v119, v119, v169
	v_lshlrev_b32_e32 v168, 16, v223
	v_and_b32_e32 v169, 0xffff0000, v223
	v_mul_f32_e32 v120, v120, v168
	v_mul_f32_e32 v121, v121, v169
	v_cvt_pk_bf16_f32 v118, v118, v119
	v_cvt_pk_bf16_f32 v119, v120, v121
	v_or_b32_e32 v120, s16, v176
	v_ashrrev_i32_e32 v121, 31, v120
	v_lshlrev_b64 v[120:121], 12, v[120:121]
	v_lshl_add_u64 v[120:121], v[162:163], 0, v[120:121]
	global_store_dwordx2 v[120:121], v[118:119], off
	v_add_f32_e32 v114, v114, v197
	v_add_f32_e32 v115, v115, v197
	v_add_f32_e32 v116, v116, v197
	v_add_f32_e32 v117, v117, v197
	v_lshlrev_b32_e32 v168, 16, v224
	v_and_b32_e32 v169, 0xffff0000, v224
	v_mul_f32_e32 v114, v114, v168
	v_mul_f32_e32 v115, v115, v169
	v_lshlrev_b32_e32 v168, 16, v225
	v_and_b32_e32 v169, 0xffff0000, v225
	v_mul_f32_e32 v116, v116, v168
	v_mul_f32_e32 v117, v117, v169
	v_cvt_pk_bf16_f32 v114, v114, v115
	v_cvt_pk_bf16_f32 v115, v116, v117
	global_store_dwordx2 v[120:121], v[114:115], off offset:32
	s_waitcnt vmcnt(19)
	v_add_f32_e32 v110, v110, v213
	v_add_f32_e32 v111, v111, v213
	v_add_f32_e32 v112, v112, v213
	v_add_f32_e32 v113, v113, v213
	v_lshlrev_b32_e32 v168, 16, v226
	v_and_b32_e32 v169, 0xffff0000, v226
	v_mul_f32_e32 v110, v110, v168
	v_mul_f32_e32 v111, v111, v169
	v_lshlrev_b32_e32 v168, 16, v227
	v_and_b32_e32 v169, 0xffff0000, v227
	v_mul_f32_e32 v112, v112, v168
	v_mul_f32_e32 v113, v113, v169
	v_cvt_pk_bf16_f32 v110, v110, v111
	v_cvt_pk_bf16_f32 v111, v112, v113
	v_or_b32_e32 v112, s16, v177
	v_ashrrev_i32_e32 v113, 31, v112
	v_lshlrev_b64 v[112:113], 12, v[112:113]
	v_lshl_add_u64 v[112:113], v[162:163], 0, v[112:113]
	global_store_dwordx2 v[112:113], v[110:111], off
	v_add_f32_e32 v106, v106, v213
	v_add_f32_e32 v107, v107, v213
	v_add_f32_e32 v108, v108, v213
	v_add_f32_e32 v109, v109, v213
	v_lshlrev_b32_e32 v168, 16, v228
	v_and_b32_e32 v169, 0xffff0000, v228
	v_mul_f32_e32 v106, v106, v168
	v_mul_f32_e32 v107, v107, v169
	v_lshlrev_b32_e32 v168, 16, v229
	v_and_b32_e32 v169, 0xffff0000, v229
	v_mul_f32_e32 v108, v108, v168
	v_mul_f32_e32 v109, v109, v169
	v_cvt_pk_bf16_f32 v106, v106, v107
	v_cvt_pk_bf16_f32 v107, v108, v109
	global_store_dwordx2 v[112:113], v[106:107], off offset:32
	s_waitcnt vmcnt(18)
	v_add_f32_e32 v102, v102, v249
	v_add_f32_e32 v103, v103, v249
	v_add_f32_e32 v104, v104, v249
	v_add_f32_e32 v105, v105, v249
	v_lshlrev_b32_e32 v168, 16, v230
	v_and_b32_e32 v169, 0xffff0000, v230
	v_mul_f32_e32 v102, v102, v168
	v_mul_f32_e32 v103, v103, v169
	v_lshlrev_b32_e32 v168, 16, v231
	v_and_b32_e32 v169, 0xffff0000, v231
	v_mul_f32_e32 v104, v104, v168
	v_mul_f32_e32 v105, v105, v169
	v_cvt_pk_bf16_f32 v102, v102, v103
	v_cvt_pk_bf16_f32 v103, v104, v105
	v_or_b32_e32 v104, s16, v178
	v_ashrrev_i32_e32 v105, 31, v104
	v_lshlrev_b64 v[104:105], 12, v[104:105]
	v_lshl_add_u64 v[104:105], v[162:163], 0, v[104:105]
	global_store_dwordx2 v[104:105], v[102:103], off
	v_add_f32_e32 v98, v98, v249
	v_add_f32_e32 v99, v99, v249
	v_add_f32_e32 v100, v100, v249
	v_add_f32_e32 v101, v101, v249
	v_lshlrev_b32_e32 v168, 16, v232
	v_and_b32_e32 v169, 0xffff0000, v232
	v_mul_f32_e32 v98, v98, v168
	v_mul_f32_e32 v99, v99, v169
	v_lshlrev_b32_e32 v168, 16, v233
	v_and_b32_e32 v169, 0xffff0000, v233
	v_mul_f32_e32 v100, v100, v168
	v_mul_f32_e32 v101, v101, v169
	v_cvt_pk_bf16_f32 v98, v98, v99
	v_cvt_pk_bf16_f32 v99, v100, v101
	global_store_dwordx2 v[104:105], v[98:99], off offset:32
	s_waitcnt vmcnt(17)
	v_add_f32_e32 v94, v94, v214
	v_add_f32_e32 v95, v95, v214
	v_add_f32_e32 v96, v96, v214
	v_add_f32_e32 v97, v97, v214
	v_lshlrev_b32_e32 v168, 16, v234
	v_and_b32_e32 v169, 0xffff0000, v234
	v_mul_f32_e32 v94, v94, v168
	v_mul_f32_e32 v95, v95, v169
	v_lshlrev_b32_e32 v168, 16, v235
	v_and_b32_e32 v169, 0xffff0000, v235
	v_mul_f32_e32 v96, v96, v168
	v_mul_f32_e32 v97, v97, v169
	v_cvt_pk_bf16_f32 v94, v94, v95
	v_cvt_pk_bf16_f32 v95, v96, v97
	v_or_b32_e32 v96, s16, v179
	v_ashrrev_i32_e32 v97, 31, v96
	v_lshlrev_b64 v[96:97], 12, v[96:97]
	v_lshl_add_u64 v[96:97], v[162:163], 0, v[96:97]
	global_store_dwordx2 v[96:97], v[94:95], off
	v_add_f32_e32 v90, v90, v214
	v_add_f32_e32 v91, v91, v214
	v_add_f32_e32 v92, v92, v214
	v_add_f32_e32 v93, v93, v214
	v_lshlrev_b32_e32 v168, 16, v236
	v_and_b32_e32 v169, 0xffff0000, v236
	v_mul_f32_e32 v90, v90, v168
	v_mul_f32_e32 v91, v91, v169
	v_lshlrev_b32_e32 v168, 16, v237
	v_and_b32_e32 v169, 0xffff0000, v237
	v_mul_f32_e32 v92, v92, v168
	v_mul_f32_e32 v93, v93, v169
	v_cvt_pk_bf16_f32 v90, v90, v91
	v_cvt_pk_bf16_f32 v91, v92, v93
	global_store_dwordx2 v[96:97], v[90:91], off offset:32
	s_waitcnt vmcnt(16)
	v_add_f32_e32 v86, v86, v215
	v_add_f32_e32 v87, v87, v215
	v_add_f32_e32 v88, v88, v215
	v_add_f32_e32 v89, v89, v215
	v_lshlrev_b32_e32 v168, 16, v238
	v_and_b32_e32 v169, 0xffff0000, v238
	v_mul_f32_e32 v86, v86, v168
	v_mul_f32_e32 v87, v87, v169
	v_lshlrev_b32_e32 v168, 16, v239
	v_and_b32_e32 v169, 0xffff0000, v239
	v_mul_f32_e32 v88, v88, v168
	v_mul_f32_e32 v89, v89, v169
	v_cvt_pk_bf16_f32 v86, v86, v87
	v_cvt_pk_bf16_f32 v87, v88, v89
	v_or_b32_e32 v88, s16, v180
	v_ashrrev_i32_e32 v89, 31, v88
	v_lshlrev_b64 v[88:89], 12, v[88:89]
	v_lshl_add_u64 v[88:89], v[162:163], 0, v[88:89]
	global_store_dwordx2 v[88:89], v[86:87], off
	v_add_f32_e32 v82, v82, v215
	v_add_f32_e32 v83, v83, v215
	v_add_f32_e32 v84, v84, v215
	v_add_f32_e32 v85, v85, v215
	v_lshlrev_b32_e32 v168, 16, v240
	v_and_b32_e32 v169, 0xffff0000, v240
	v_mul_f32_e32 v82, v82, v168
	v_mul_f32_e32 v83, v83, v169
	v_lshlrev_b32_e32 v168, 16, v241
	v_and_b32_e32 v169, 0xffff0000, v241
	v_mul_f32_e32 v84, v84, v168
	v_mul_f32_e32 v85, v85, v169
	v_cvt_pk_bf16_f32 v82, v82, v83
	v_cvt_pk_bf16_f32 v83, v84, v85
	global_store_dwordx2 v[88:89], v[82:83], off offset:32
	s_waitcnt vmcnt(15)
	v_add_f32_e32 v78, v78, v216
	v_add_f32_e32 v79, v79, v216
	v_add_f32_e32 v80, v80, v216
	v_add_f32_e32 v81, v81, v216
	v_lshlrev_b32_e32 v168, 16, v250
	v_and_b32_e32 v169, 0xffff0000, v250
	v_mul_f32_e32 v78, v78, v168
	v_mul_f32_e32 v79, v79, v169
	v_lshlrev_b32_e32 v168, 16, v251
	v_and_b32_e32 v169, 0xffff0000, v251
	v_mul_f32_e32 v80, v80, v168
	v_mul_f32_e32 v81, v81, v169
	v_cvt_pk_bf16_f32 v78, v78, v79
	v_cvt_pk_bf16_f32 v79, v80, v81
	v_or_b32_e32 v80, s16, v181
	v_ashrrev_i32_e32 v81, 31, v80
	v_lshlrev_b64 v[80:81], 12, v[80:81]
	v_lshl_add_u64 v[80:81], v[162:163], 0, v[80:81]
	global_store_dwordx2 v[80:81], v[78:79], off
	v_add_f32_e32 v74, v74, v216
	v_add_f32_e32 v75, v75, v216
	v_add_f32_e32 v76, v76, v216
	v_add_f32_e32 v77, v77, v216
	v_lshlrev_b32_e32 v168, 16, v252
	v_and_b32_e32 v169, 0xffff0000, v252
	v_mul_f32_e32 v74, v74, v168
	v_mul_f32_e32 v75, v75, v169
	v_lshlrev_b32_e32 v168, 16, v253
	v_and_b32_e32 v169, 0xffff0000, v253
	v_mul_f32_e32 v76, v76, v168
	v_mul_f32_e32 v77, v77, v169
	v_cvt_pk_bf16_f32 v74, v74, v75
	v_cvt_pk_bf16_f32 v75, v76, v77
	global_store_dwordx2 v[80:81], v[74:75], off offset:32
	s_waitcnt vmcnt(14)
	v_add_f32_e32 v70, v70, v217
	v_add_f32_e32 v71, v71, v217
	v_add_f32_e32 v72, v72, v217
	v_add_f32_e32 v73, v73, v217
	v_lshlrev_b32_e32 v168, 16, v254
	v_and_b32_e32 v169, 0xffff0000, v254
	v_mul_f32_e32 v70, v70, v168
	v_mul_f32_e32 v71, v71, v169
	v_lshlrev_b32_e32 v168, 16, v255
	v_and_b32_e32 v169, 0xffff0000, v255
	v_mul_f32_e32 v72, v72, v168
	v_mul_f32_e32 v73, v73, v169
	v_cvt_pk_bf16_f32 v70, v70, v71
	v_cvt_pk_bf16_f32 v71, v72, v73
	v_or_b32_e32 v72, s16, v174
	v_ashrrev_i32_e32 v73, 31, v72
	v_lshlrev_b64 v[72:73], 12, v[72:73]
	v_lshl_add_u64 v[72:73], v[162:163], 0, v[72:73]
	global_store_dwordx2 v[72:73], v[70:71], off
	v_add_f32_e32 v66, v66, v217
	v_add_f32_e32 v67, v67, v217
	v_add_f32_e32 v68, v68, v217
	v_add_f32_e32 v69, v69, v217
	v_lshlrev_b32_e32 v168, 16, v194
	v_and_b32_e32 v169, 0xffff0000, v194
	v_mul_f32_e32 v66, v66, v168
	v_mul_f32_e32 v67, v67, v169
	v_lshlrev_b32_e32 v168, 16, v195
	v_and_b32_e32 v169, 0xffff0000, v195
	v_mul_f32_e32 v68, v68, v168
	v_mul_f32_e32 v69, v69, v169
	v_cvt_pk_bf16_f32 v66, v66, v67
	v_cvt_pk_bf16_f32 v67, v68, v69
	global_store_dwordx2 v[72:73], v[66:67], off offset:32
	s_cbranch_vccz .LBB11_1438
